# P7 cross-attention q-prep: the 7 serialized pairs of q-gain loads (each waited with vmcnt(0)) are issued ahead, 9 at the first site and the rest as registers free up
# speedup vs baseline: 1.0022x; 1.0022x over previous
.LBB0_1243:
	s_ashr_i32 s12, s10, 5
	s_bfe_u32 s11, s10, 0x20003
	s_lshl_b32 s14, s12, 2
	s_or_b32 s14, s14, s11
	s_ashr_i32 s15, s14, 31
	s_lshl_b64 s[14:15], s[14:15], 16
	v_lshl_add_u64 v[0:1], v[114:115], 0, s[14:15]
	v_mov_b32_e32 v123, v113
	v_lshl_add_u64 v[2:3], v[0:1], 0, v[122:123]
	v_mov_b32_e32 v125, v113
	v_mov_b32_e32 v127, v113
	s_barrier
	v_lshl_add_u64 v[4:5], v[0:1], 0, v[124:125]
	global_load_dwordx4 v[12:15], v[2:3], off
	global_load_dwordx4 v[16:19], v[4:5], off
	v_lshl_add_u64 v[2:3], v[0:1], 0, v[126:127]
	v_mov_b32_e32 v129, v113
	v_mov_b32_e32 v131, v113
	s_lshl_b32 s4, s10, 8
	v_lshl_add_u64 v[4:5], v[0:1], 0, v[128:129]
	global_load_dwordx4 v[20:23], v[2:3], off
	global_load_dwordx4 v[24:27], v[4:5], off
	v_lshl_add_u64 v[2:3], v[0:1], 0, v[130:131]
	v_mov_b32_e32 v133, v113
	v_mov_b32_e32 v135, v113
	v_mov_b32_e32 v137, v113
	s_ashr_i32 s13, s12, 31
	v_lshl_add_u64 v[4:5], v[0:1], 0, v[132:133]
	global_load_dwordx4 v[28:31], v[2:3], off
	global_load_dwordx4 v[44:47], v[4:5], off
	v_lshl_add_u64 v[2:3], v[0:1], 0, v[134:135]
	v_lshl_add_u64 v[0:1], v[0:1], 0, v[136:137]
	v_lshl_add_u64 v[48:49], v[116:117], 0, s[14:15]
	v_mov_b32_e32 v139, v113
	s_and_b32 s4, s4, 0x700
	global_load_dwordx4 v[58:61], v[2:3], off
	global_load_dwordx4 v[62:65], v[0:1], off
	v_lshl_add_u64 v[0:1], v[48:49], 0, v[138:139]
	v_add_u32_e32 v112, s4, v160
	s_lshl_b64 s[12:13], s[12:13], 11
	global_load_dwordx4 v[66:69], v[0:1], off
	v_lshl_add_u64 v[0:1], s[12:13], 0, v[112:113]
	v_lshl_add_u64 v[2:3], v[0:1], 2, s[0:1]
	global_load_dword v78, v[2:3], off
	s_lshl_b32 s4, s11, 8
	v_lshl_add_u64 v[2:3], v[118:119], 0, s[4:5]
	v_lshlrev_b64 v[156:157], 10, v[0:1]
	v_lshl_add_u64 v[52:53], v[2:3], 0, v[156:157]
	global_load_dwordx4 v[70:73], v[52:53], off
	v_add_co_u32_e32 v54, vcc, s6, v52
	v_mov_b32_e32 v141, v113
	s_nop 0
	v_addc_co_u32_e32 v55, vcc, 0, v53, vcc
	v_add_co_u32_e32 v56, vcc, s7, v52
	v_mov_b32_e32 v143, v113
	s_nop 0
	v_addc_co_u32_e32 v57, vcc, 0, v53, vcc
	v_mov_b32_e32 v145, v113
	v_lshl_add_u64 v[4:5], v[48:49], 0, v[140:141]
	v_lshl_add_u64 v[6:7], v[48:49], 0, v[142:143]
	v_lshl_add_u64 v[8:9], v[48:49], 0, v[144:145]
	v_add_co_u32_e32 v50, vcc, s8, v52
	global_load_dwordx4 v[32:35], v[54:55], off
	global_load_dwordx4 v[36:39], v[56:57], off
	v_addc_co_u32_e32 v51, vcc, 0, v53, vcc
	global_load_dwordx4 v[0:3], v[4:5], off
	global_load_dwordx4 v[40:43], v[50:51], off
	s_nop 0
	global_load_dwordx4 v[4:7], v[6:7], off
	s_nop 0
	global_load_dwordx4 v[8:11], v[8:9], off
	v_mov_b32_e32 v147, v113
	v_mov_b32_e32 v151, v113
	v_mov_b32_e32 v149, v113
	v_lshl_add_u64 v[74:75], v[48:49], 0, v[146:147]
	v_mov_b32_e32 v153, v113
	v_lshl_add_u64 v[76:77], v[48:49], 0, v[148:149]
	s_lshl_b32 s4, s11, 7
	s_mov_b32 s11, 8
	s_waitcnt vmcnt(16)
	ds_write_b128 v164, v[12:15]
	s_waitcnt vmcnt(15)
	ds_write_b128 v165, v[16:19]
	s_waitcnt vmcnt(14)
	ds_write_b128 v166, v[20:23]
	s_waitcnt vmcnt(13)
	ds_write_b128 v167, v[24:27]
	s_waitcnt vmcnt(12)
	ds_write_b128 v168, v[28:31]
	s_waitcnt vmcnt(11)
	ds_write_b128 v169, v[44:47]
	s_waitcnt vmcnt(10)
	ds_write_b128 v170, v[58:61]
	s_waitcnt vmcnt(9)
	ds_write_b128 v171, v[62:65]
	s_waitcnt vmcnt(8)
	ds_write_b128 v172, v[66:69]
	v_lshl_add_u64 v[28:29], v[48:49], 0, v[150:151]
	global_load_dwordx4 v[16:19], v[74:75], off
	global_load_dwordx4 v[12:15], v[76:77], off
	v_lshl_add_u64 v[30:31], v[48:49], 0, v[152:153]
	s_waitcnt vmcnt(9)
	v_fmamk_f32 v20, v78, 0x3a000000, v180
	v_mul_f32_e32 v21, 0x4b800000, v20
	v_cmp_gt_f32_e32 vcc, s6, v20
	s_waitcnt vmcnt(7)
	v_lshlrev_b32_e32 v65, 16, v32
	v_cndmask_b32_e32 v20, v20, v21, vcc
	v_rsq_f32_e32 v44, v20
	global_load_dwordx4 v[20:23], v[28:29], off
	global_load_dwordx4 v[24:27], v[30:31], off
	global_load_dwordx4 v[66:69], v[54:55], off offset:32
	global_load_dwordx4 v[74:77], v[50:51], off offset:32
	v_mul_f32_e32 v28, 0x45800000, v44
	v_cndmask_b32_e32 v48, v44, v28, vcc
	v_lshlrev_b32_e32 v28, 16, v70
	v_add_f32_e32 v58, 0, v28
	v_and_b32_e32 v28, 0xffff0000, v70
	v_add_f32_e32 v59, 0, v28
	v_lshlrev_b32_e32 v28, 16, v71
	v_add_f32_e32 v60, 0, v28
	v_and_b32_e32 v28, 0xffff0000, v71
	v_add_f32_e32 v49, 0, v28
	v_lshlrev_b32_e32 v28, 16, v72
	v_add_f32_e32 v61, 0, v28
	v_and_b32_e32 v28, 0xffff0000, v72
	v_add_f32_e32 v62, 0, v28
	v_lshlrev_b32_e32 v28, 16, v73
	global_load_dwordx4 v[44:47], v[52:53], off offset:32
	global_load_dwordx4 v[78:81], v[52:53], off offset:64
	v_add_f32_e32 v63, 0, v28
	v_and_b32_e32 v28, 0xffff0000, v73
	v_add_f32_e32 v64, 0, v28
	global_load_dwordx4 v[28:31], v[52:53], off offset:224
	global_load_dwordx4 v[70:73], v[56:57], off offset:32
	v_and_b32_e32 v32, 0xffff0000, v32
	v_add_f32_e32 v58, v58, v65
	v_add_f32_e32 v59, v59, v32
	v_lshlrev_b32_e32 v32, 16, v33
	s_waitcnt vmcnt(14)
	v_lshlrev_b32_e32 v65, 16, v36
	v_and_b32_e32 v36, 0xffff0000, v36
	global_load_dwordx4 v[82:85], v[54:55], off offset:64
	global_load_dwordx4 v[102:105], v[54:55], off offset:128
	v_add_f32_e32 v60, v60, v32
	v_and_b32_e32 v32, 0xffff0000, v33
	v_add_f32_e32 v59, v59, v36
	v_lshlrev_b32_e32 v36, 16, v37
	v_add_f32_e32 v49, v49, v32
	v_lshlrev_b32_e32 v32, 16, v34
	v_add_f32_e32 v58, v58, v65
	v_add_f32_e32 v60, v60, v36
	v_and_b32_e32 v36, 0xffff0000, v37
	s_waitcnt vmcnt(14)
	v_lshlrev_b32_e32 v65, 16, v40
	v_and_b32_e32 v40, 0xffff0000, v40
	v_add_f32_e32 v61, v61, v32
	v_add_f32_e32 v49, v49, v36
	v_lshlrev_b32_e32 v36, 16, v38
	v_add_f32_e32 v40, v59, v40
	v_lshlrev_b32_e32 v59, 16, v41
	v_and_b32_e32 v41, 0xffff0000, v41
	v_add_f32_e32 v61, v61, v36
	v_add_f32_e32 v41, v49, v41
	v_lshlrev_b32_e32 v49, 16, v42
	v_add_f32_e32 v61, v61, v49
	v_mul_f32_e32 v49, v48, v40
	v_and_b32_e32 v32, 0xffff0000, v34
	v_add_f32_e32 v62, v62, v32
	v_lshlrev_b32_e32 v32, 16, v35
	v_and_b32_e32 v36, 0xffff0000, v38
	v_add_f32_e32 v63, v63, v32
	v_and_b32_e32 v32, 0xffff0000, v35
	v_add_f32_e32 v62, v62, v36
	v_lshlrev_b32_e32 v36, 16, v39
	v_and_b32_e32 v42, 0xffff0000, v42
	v_add_f32_e32 v64, v64, v32
	v_add_f32_e32 v63, v63, v36
	v_and_b32_e32 v36, 0xffff0000, v39
	v_add_f32_e32 v62, v62, v42
	v_lshlrev_b32_e32 v42, 16, v43
	v_add_f32_e32 v64, v64, v36
	v_add_f32_e32 v63, v63, v42
	v_and_b32_e32 v42, 0xffff0000, v43
	v_add_f32_e32 v59, v60, v59
	v_add_f32_e32 v43, v64, v42
	v_mul_f32_e32 v60, v48, v41
	v_mul_f32_e32 v64, v48, v43
	v_add_f32_e32 v58, v58, v65
	global_load_dwordx4 v[90:93], v[52:53], off offset:96
	global_load_dwordx4 v[98:101], v[52:53], off offset:128
	global_load_dwordx4 v[32:35], v[54:55], off offset:224
	global_load_dwordx4 v[36:39], v[56:57], off offset:224
	s_waitcnt vmcnt(11)
	v_lshlrev_b32_e32 v86, 16, v66
	v_and_b32_e32 v66, 0xffff0000, v66
	global_load_dwordx4 v[106:109], v[56:57], off offset:128
	v_mul_f32_e32 v58, v48, v58
	v_mul_f32_e32 v42, v49, v49
	v_fmac_f32_e32 v42, v58, v58
	v_mul_f32_e32 v59, v48, v59
	v_fmac_f32_e32 v42, v59, v59
	v_fmac_f32_e32 v42, v60, v60
	v_mul_f32_e32 v61, v48, v61
	v_fmac_f32_e32 v42, v61, v61
	v_mul_f32_e32 v62, v48, v62
	v_fmac_f32_e32 v42, v62, v62
	v_mul_f32_e32 v63, v48, v63
	v_fmac_f32_e32 v42, v63, v63
	v_fmac_f32_e32 v42, v64, v64
	s_waitcnt vmcnt(10)
	v_lshlrev_b32_e32 v40, 16, v44
	v_add_f32_e32 v40, 0, v40
	v_add_f32_e32 v40, v40, v86
	global_load_dwordx4 v[86:89], v[56:57], off offset:64
	v_and_b32_e32 v41, 0xffff0000, v44
	v_add_f32_e32 v41, 0, v41
	v_lshlrev_b32_e32 v43, 16, v45
	v_add_f32_e32 v43, 0, v43
	v_and_b32_e32 v44, 0xffff0000, v45
	v_add_f32_e32 v41, v41, v66
	v_lshlrev_b32_e32 v66, 16, v67
	v_add_f32_e32 v44, 0, v44
	v_lshlrev_b32_e32 v45, 16, v46
	v_add_f32_e32 v43, v43, v66
	v_and_b32_e32 v66, 0xffff0000, v67
	v_add_f32_e32 v45, 0, v45
	v_and_b32_e32 v46, 0xffff0000, v46
	v_add_f32_e32 v44, v44, v66
	v_lshlrev_b32_e32 v66, 16, v68
	v_add_f32_e32 v46, 0, v46
	v_lshlrev_b32_e32 v65, 16, v47
	v_add_f32_e32 v45, v45, v66
	v_and_b32_e32 v66, 0xffff0000, v68
	v_add_f32_e32 v65, 0, v65
	v_and_b32_e32 v47, 0xffff0000, v47
	v_add_f32_e32 v46, v46, v66
	v_lshlrev_b32_e32 v66, 16, v69
	v_add_f32_e32 v47, 0, v47
	v_add_f32_e32 v65, v65, v66
	v_and_b32_e32 v66, 0xffff0000, v69
	v_add_f32_e32 v47, v47, v66
	s_waitcnt vmcnt(8)
	v_lshlrev_b32_e32 v66, 16, v70
	v_add_f32_e32 v40, v40, v66
	v_and_b32_e32 v66, 0xffff0000, v70
	v_add_f32_e32 v41, v41, v66
	v_lshlrev_b32_e32 v66, 16, v71
	v_add_f32_e32 v43, v43, v66
	v_and_b32_e32 v66, 0xffff0000, v71
	v_add_f32_e32 v44, v44, v66
	v_lshlrev_b32_e32 v66, 16, v72
	v_add_f32_e32 v45, v45, v66
	v_and_b32_e32 v66, 0xffff0000, v72
	v_add_f32_e32 v46, v46, v66
	v_lshlrev_b32_e32 v66, 16, v73
	v_add_f32_e32 v65, v65, v66
	v_and_b32_e32 v66, 0xffff0000, v73
	global_load_dwordx4 v[70:73], v[50:51], off offset:64
	v_add_f32_e32 v47, v47, v66
	v_lshlrev_b32_e32 v66, 16, v74
	v_add_f32_e32 v40, v40, v66
	v_and_b32_e32 v66, 0xffff0000, v74
	v_add_f32_e32 v41, v41, v66
	v_lshlrev_b32_e32 v66, 16, v75
	v_add_f32_e32 v43, v43, v66
	v_and_b32_e32 v66, 0xffff0000, v75
	v_add_f32_e32 v66, v44, v66
	v_lshlrev_b32_e32 v44, 16, v76
	v_add_f32_e32 v67, v45, v44
	v_and_b32_e32 v44, 0xffff0000, v76
	v_add_f32_e32 v68, v46, v44
	v_lshlrev_b32_e32 v44, 16, v77
	v_add_f32_e32 v69, v65, v44
	v_and_b32_e32 v44, 0xffff0000, v77
	v_add_f32_e32 v74, v47, v44
	v_mul_f32_e32 v44, v48, v40
	v_lshlrev_b32_e32 v40, 16, v78
	v_mul_f32_e32 v45, v48, v41
	v_mul_f32_e32 v46, v48, v43
	v_add_f32_e32 v40, 0, v40
	v_and_b32_e32 v41, 0xffff0000, v78
	v_lshlrev_b32_e32 v43, 16, v79
	s_waitcnt vmcnt(8)
	v_lshlrev_b32_e32 v78, 16, v82
	v_mul_f32_e32 v65, v48, v67
	v_mul_f32_e32 v67, v48, v69
	v_add_f32_e32 v43, 0, v43
	v_and_b32_e32 v69, 0xffff0000, v79
	v_add_f32_e32 v40, v40, v78
	v_and_b32_e32 v78, 0xffff0000, v82
	v_lshlrev_b32_e32 v82, 16, v83
	v_mul_f32_e32 v47, v48, v66
	v_mul_f32_e32 v66, v48, v68
	v_mul_f32_e32 v68, v48, v74
	v_add_f32_e32 v69, 0, v69
	v_lshlrev_b32_e32 v74, 16, v80
	v_add_f32_e32 v43, v43, v82
	v_and_b32_e32 v82, 0xffff0000, v83
	v_add_f32_e32 v74, 0, v74
	v_and_b32_e32 v75, 0xffff0000, v80
	v_add_f32_e32 v69, v69, v82
	v_lshlrev_b32_e32 v82, 16, v84
	v_add_f32_e32 v41, 0, v41
	v_add_f32_e32 v75, 0, v75
	v_lshlrev_b32_e32 v76, 16, v81
	v_add_f32_e32 v74, v74, v82
	v_and_b32_e32 v82, 0xffff0000, v84
	v_add_f32_e32 v76, 0, v76
	v_and_b32_e32 v77, 0xffff0000, v81
	v_add_f32_e32 v41, v41, v78
	global_load_dwordx4 v[78:81], v[54:55], off offset:96
	v_add_f32_e32 v75, v75, v82
	v_lshlrev_b32_e32 v82, 16, v85
	v_add_f32_e32 v77, 0, v77
	v_add_f32_e32 v76, v76, v82
	v_and_b32_e32 v82, 0xffff0000, v85
	v_add_f32_e32 v77, v77, v82
	s_waitcnt vmcnt(2)
	v_lshlrev_b32_e32 v82, 16, v86
	v_add_f32_e32 v40, v40, v82
	v_and_b32_e32 v82, 0xffff0000, v86
	v_add_f32_e32 v41, v41, v82
	global_load_dwordx4 v[82:85], v[56:57], off offset:96
	v_lshlrev_b32_e32 v86, 16, v87
	v_add_f32_e32 v43, v43, v86
	v_and_b32_e32 v86, 0xffff0000, v87
	v_add_f32_e32 v69, v69, v86
	v_lshlrev_b32_e32 v86, 16, v88
	v_add_f32_e32 v74, v74, v86
	v_and_b32_e32 v86, 0xffff0000, v88
	v_add_f32_e32 v75, v75, v86
	v_lshlrev_b32_e32 v86, 16, v89
	v_add_f32_e32 v76, v76, v86
	v_and_b32_e32 v86, 0xffff0000, v89
	v_add_f32_e32 v77, v77, v86
	v_fmac_f32_e32 v42, v44, v44
	v_fmac_f32_e32 v42, v45, v45
	v_fmac_f32_e32 v42, v46, v46
	v_fmac_f32_e32 v42, v47, v47
	s_waitcnt vmcnt(2)
	v_lshlrev_b32_e32 v86, 16, v70
	v_add_f32_e32 v40, v40, v86
	global_load_dwordx4 v[86:89], v[50:51], off offset:96
	v_and_b32_e32 v70, 0xffff0000, v70
	v_add_f32_e32 v41, v41, v70
	v_lshlrev_b32_e32 v70, 16, v71
	v_add_f32_e32 v43, v43, v70
	v_and_b32_e32 v70, 0xffff0000, v71
	v_add_f32_e32 v94, v69, v70
	v_lshlrev_b32_e32 v69, 16, v72
	v_add_f32_e32 v74, v74, v69
	v_and_b32_e32 v69, 0xffff0000, v72
	v_add_f32_e32 v75, v75, v69
	v_lshlrev_b32_e32 v69, 16, v73
	v_add_f32_e32 v76, v76, v69
	v_and_b32_e32 v69, 0xffff0000, v73
	v_mul_f32_e32 v70, v48, v41
	v_and_b32_e32 v41, 0xffff0000, v90
	v_add_f32_e32 v77, v77, v69
	v_mul_f32_e32 v71, v48, v43
	v_mul_f32_e32 v72, v48, v94
	v_add_f32_e32 v41, 0, v41
	v_lshlrev_b32_e32 v43, 16, v91
	v_mul_f32_e32 v73, v48, v74
	v_mul_f32_e32 v74, v48, v75
	v_mul_f32_e32 v75, v48, v76
	v_mul_f32_e32 v76, v48, v77
	v_add_f32_e32 v43, 0, v43
	v_and_b32_e32 v77, 0xffff0000, v91
	v_mul_f32_e32 v69, v48, v40
	v_lshlrev_b32_e32 v40, 16, v90
	v_add_f32_e32 v77, 0, v77
	v_lshlrev_b32_e32 v90, 16, v92
	v_add_f32_e32 v90, 0, v90
	v_and_b32_e32 v91, 0xffff0000, v92
	v_add_f32_e32 v91, 0, v91
	v_lshlrev_b32_e32 v92, 16, v93
	v_add_f32_e32 v92, 0, v92
	v_and_b32_e32 v93, 0xffff0000, v93
	v_add_f32_e32 v93, 0, v93
	v_add_f32_e32 v40, 0, v40
	v_fmac_f32_e32 v42, v65, v65
	v_fmac_f32_e32 v42, v66, v66
	v_fmac_f32_e32 v42, v67, v67
	v_fmac_f32_e32 v42, v68, v68
	v_fmac_f32_e32 v42, v69, v69
	v_fmac_f32_e32 v42, v70, v70
	v_fmac_f32_e32 v42, v71, v71
	v_fmac_f32_e32 v42, v72, v72
	v_fmac_f32_e32 v42, v73, v73
	v_fmac_f32_e32 v42, v74, v74
	v_fmac_f32_e32 v42, v75, v75
	s_waitcnt vmcnt(2)
	v_lshlrev_b32_e32 v94, 16, v78
	v_and_b32_e32 v78, 0xffff0000, v78
	v_add_f32_e32 v41, v41, v78
	v_lshlrev_b32_e32 v78, 16, v79
	v_add_f32_e32 v43, v43, v78
	v_and_b32_e32 v78, 0xffff0000, v79
	v_add_f32_e32 v77, v77, v78
	v_lshlrev_b32_e32 v78, 16, v80
	v_add_f32_e32 v78, v90, v78
	v_and_b32_e32 v79, 0xffff0000, v80
	v_add_f32_e32 v79, v91, v79
	s_waitcnt vmcnt(1)
	v_lshlrev_b32_e32 v90, 16, v82
	v_and_b32_e32 v82, 0xffff0000, v82
	v_add_f32_e32 v41, v41, v82
	v_lshlrev_b32_e32 v82, 16, v83
	v_add_f32_e32 v43, v43, v82
	v_and_b32_e32 v82, 0xffff0000, v83
	v_add_f32_e32 v77, v77, v82
	v_lshlrev_b32_e32 v82, 16, v84
	v_lshlrev_b32_e32 v80, 16, v81
	v_add_f32_e32 v78, v78, v82
	v_and_b32_e32 v82, 0xffff0000, v84
	v_add_f32_e32 v80, v92, v80
	v_and_b32_e32 v81, 0xffff0000, v81
	v_add_f32_e32 v79, v79, v82
	v_lshlrev_b32_e32 v82, 16, v85
	v_add_f32_e32 v81, v93, v81
	v_add_f32_e32 v84, v80, v82
	v_and_b32_e32 v80, 0xffff0000, v85
	v_add_f32_e32 v85, v81, v80
	global_load_dwordx4 v[80:83], v[50:51], off offset:128
	v_add_f32_e32 v40, v40, v94
	v_add_f32_e32 v40, v40, v90
	s_waitcnt vmcnt(1)
	v_lshlrev_b32_e32 v90, 16, v86
	v_and_b32_e32 v86, 0xffff0000, v86
	v_add_f32_e32 v41, v41, v86
	v_lshlrev_b32_e32 v86, 16, v87
	v_add_f32_e32 v43, v43, v86
	v_and_b32_e32 v86, 0xffff0000, v87
	v_add_f32_e32 v86, v77, v86
	v_lshlrev_b32_e32 v77, 16, v88
	v_add_f32_e32 v87, v78, v77
	v_and_b32_e32 v77, 0xffff0000, v88
	v_add_f32_e32 v88, v79, v77
	v_lshlrev_b32_e32 v77, 16, v89
	v_mul_f32_e32 v94, v48, v88
	v_and_b32_e32 v88, 0xffff0000, v99
	v_add_f32_e32 v40, v40, v90
	v_add_f32_e32 v84, v84, v77
	v_and_b32_e32 v77, 0xffff0000, v89
	v_add_f32_e32 v97, 0, v88
	v_lshlrev_b32_e32 v88, 16, v100
	v_add_f32_e32 v85, v85, v77
	v_mul_f32_e32 v77, v48, v40
	v_mul_f32_e32 v78, v48, v41
	v_lshlrev_b32_e32 v40, 16, v98
	v_and_b32_e32 v41, 0xffff0000, v98
	v_add_f32_e32 v98, 0, v88
	v_and_b32_e32 v88, 0xffff0000, v100
	v_mul_f32_e32 v79, v48, v43
	v_mul_f32_e32 v92, v48, v86
	v_mul_f32_e32 v93, v48, v87
	v_mul_f32_e32 v95, v48, v84
	v_mul_f32_e32 v96, v48, v85
	v_lshlrev_b32_e32 v43, 16, v99
	global_load_dwordx4 v[84:87], v[52:53], off offset:160
	v_add_f32_e32 v99, 0, v88
	v_lshlrev_b32_e32 v88, 16, v101
	v_add_f32_e32 v100, 0, v88
	v_and_b32_e32 v88, 0xffff0000, v101
	v_add_f32_e32 v40, 0, v40
	v_add_f32_e32 v101, 0, v88
	v_lshlrev_b32_e32 v88, 16, v102
	v_add_f32_e32 v41, 0, v41
	v_add_f32_e32 v40, v40, v88
	v_and_b32_e32 v88, 0xffff0000, v102
	v_add_f32_e32 v43, 0, v43
	v_add_f32_e32 v41, v41, v88
	v_lshlrev_b32_e32 v102, 16, v103
	global_load_dwordx4 v[88:91], v[54:55], off offset:160
	v_add_f32_e32 v43, v43, v102
	v_and_b32_e32 v102, 0xffff0000, v103
	v_add_f32_e32 v97, v97, v102
	v_lshlrev_b32_e32 v102, 16, v104
	v_add_f32_e32 v102, v98, v102
	v_and_b32_e32 v98, 0xffff0000, v104
	v_add_f32_e32 v103, v99, v98
	v_lshlrev_b32_e32 v98, 16, v105
	v_add_f32_e32 v104, v100, v98
	v_and_b32_e32 v98, 0xffff0000, v105
	v_add_f32_e32 v105, v101, v98
	v_lshlrev_b32_e32 v98, 16, v106
	v_add_f32_e32 v40, v40, v98
	v_and_b32_e32 v98, 0xffff0000, v106
	v_add_f32_e32 v41, v41, v98
	global_load_dwordx4 v[98:101], v[56:57], off offset:160
	v_lshlrev_b32_e32 v106, 16, v107
	v_add_f32_e32 v43, v43, v106
	v_and_b32_e32 v106, 0xffff0000, v107
	v_add_f32_e32 v97, v97, v106
	v_lshlrev_b32_e32 v106, 16, v108
	v_add_f32_e32 v106, v102, v106
	v_and_b32_e32 v102, 0xffff0000, v108
	v_add_f32_e32 v107, v103, v102
	v_lshlrev_b32_e32 v102, 16, v109
	v_add_f32_e32 v108, v104, v102
	v_and_b32_e32 v102, 0xffff0000, v109
	v_add_f32_e32 v109, v105, v102
	v_fmac_f32_e32 v42, v76, v76
	v_fmac_f32_e32 v42, v77, v77
	s_waitcnt vmcnt(3)
	v_lshlrev_b32_e32 v102, 16, v80
	v_add_f32_e32 v40, v40, v102
	global_load_dwordx4 v[102:105], v[50:51], off offset:160
	v_and_b32_e32 v80, 0xffff0000, v80
	v_add_f32_e32 v41, v41, v80
	v_lshlrev_b32_e32 v80, 16, v81
	v_add_f32_e32 v43, v43, v80
	v_and_b32_e32 v80, 0xffff0000, v81
	v_add_f32_e32 v80, v97, v80
	v_lshlrev_b32_e32 v81, 16, v82
	v_and_b32_e32 v82, 0xffff0000, v82
	v_lshlrev_b32_e32 v97, 16, v83
	v_and_b32_e32 v83, 0xffff0000, v83
	v_add_f32_e32 v81, v106, v81
	v_add_f32_e32 v82, v107, v82
	v_add_f32_e32 v83, v109, v83
	v_mul_f32_e32 v109, v48, v80
	v_mul_f32_e32 v110, v48, v81
	v_mul_f32_e32 v111, v48, v82
	v_mul_f32_e32 v112, v48, v83
	global_load_dwordx4 v[80:83], v[52:53], off offset:192
	v_mul_f32_e32 v106, v48, v40
	v_mul_f32_e32 v107, v48, v41
	v_add_f32_e32 v97, v108, v97
	v_mul_f32_e32 v108, v48, v43
	v_fmac_f32_e32 v42, v78, v78
	v_fmac_f32_e32 v42, v79, v79
	v_fmac_f32_e32 v42, v92, v92
	v_fmac_f32_e32 v42, v93, v93
	v_fmac_f32_e32 v42, v94, v94
	v_fmac_f32_e32 v42, v95, v95
	v_fmac_f32_e32 v42, v96, v96
	v_fmac_f32_e32 v42, v106, v106
	v_fmac_f32_e32 v42, v107, v107
	v_fmac_f32_e32 v42, v108, v108
	s_waitcnt vmcnt(4)
	v_and_b32_e32 v52, 0xffff0000, v85
	v_lshlrev_b32_e32 v40, 16, v84
	v_and_b32_e32 v41, 0xffff0000, v84
	v_add_f32_e32 v84, 0, v52
	v_lshlrev_b32_e32 v52, 16, v86
	v_lshlrev_b32_e32 v43, 16, v85
	v_add_f32_e32 v85, 0, v52
	v_and_b32_e32 v52, 0xffff0000, v86
	v_add_f32_e32 v123, 0, v52
	v_lshlrev_b32_e32 v52, 16, v87
	v_add_f32_e32 v40, 0, v40
	v_add_f32_e32 v125, 0, v52
	v_and_b32_e32 v52, 0xffff0000, v87
	v_add_f32_e32 v41, 0, v41
	s_waitcnt vmcnt(3)
	v_lshlrev_b32_e32 v86, 16, v88
	v_add_f32_e32 v127, 0, v52
	global_load_dwordx4 v[52:55], v[54:55], off offset:192
	v_add_f32_e32 v40, v40, v86
	v_and_b32_e32 v86, 0xffff0000, v88
	v_add_f32_e32 v43, 0, v43
	v_add_f32_e32 v41, v41, v86
	v_lshlrev_b32_e32 v86, 16, v89
	v_add_f32_e32 v43, v43, v86
	v_and_b32_e32 v86, 0xffff0000, v89
	v_add_f32_e32 v129, v84, v86
	v_lshlrev_b32_e32 v84, 16, v90
	v_add_f32_e32 v131, v85, v84
	global_load_dwordx4 v[84:87], v[56:57], off offset:192
	v_and_b32_e32 v88, 0xffff0000, v90
	v_add_f32_e32 v56, v123, v88
	v_and_b32_e32 v88, 0xffff0000, v91
	v_add_f32_e32 v123, v127, v88
	s_waitcnt vmcnt(4)
	v_lshlrev_b32_e32 v88, 16, v98
	v_add_f32_e32 v40, v40, v88
	v_and_b32_e32 v88, 0xffff0000, v98
	v_add_f32_e32 v41, v41, v88
	v_lshlrev_b32_e32 v88, 16, v99
	v_lshlrev_b32_e32 v57, 16, v91
	v_add_f32_e32 v43, v43, v88
	global_load_dwordx4 v[88:91], v[50:51], off offset:192
	v_and_b32_e32 v98, 0xffff0000, v99
	v_lshlrev_b32_e32 v99, 16, v100
	v_and_b32_e32 v100, 0xffff0000, v100
	v_add_f32_e32 v57, v125, v57
	v_add_f32_e32 v56, v56, v100
	v_lshlrev_b32_e32 v100, 16, v101
	v_add_f32_e32 v57, v57, v100
	v_and_b32_e32 v100, 0xffff0000, v101
	s_waitcnt vmcnt(4)
	v_lshlrev_b32_e32 v101, 16, v102
	v_add_f32_e32 v40, v40, v101
	v_and_b32_e32 v101, 0xffff0000, v102
	v_add_f32_e32 v41, v41, v101
	v_lshlrev_b32_e32 v101, 16, v103
	v_add_f32_e32 v98, v129, v98
	v_add_f32_e32 v43, v43, v101
	v_and_b32_e32 v101, 0xffff0000, v103
	v_add_f32_e32 v99, v131, v99
	v_add_f32_e32 v98, v98, v101
	v_lshlrev_b32_e32 v101, 16, v104
	v_add_f32_e32 v99, v99, v101
	v_and_b32_e32 v101, 0xffff0000, v104
	v_add_f32_e32 v56, v56, v101
	v_lshlrev_b32_e32 v101, 16, v105
	v_add_f32_e32 v100, v123, v100
	v_add_f32_e32 v57, v57, v101
	v_and_b32_e32 v101, 0xffff0000, v105
	v_add_f32_e32 v100, v100, v101
	v_mul_f32_e32 v105, v48, v98
	v_mul_f32_e32 v123, v48, v99
	v_mul_f32_e32 v129, v48, v100
	global_load_dwordx4 v[98:101], v[50:51], off offset:224
	v_mul_f32_e32 v103, v48, v41
	s_waitcnt vmcnt(4)
	v_and_b32_e32 v41, 0xffff0000, v80
	v_mul_f32_e32 v104, v48, v43
	v_mul_f32_e32 v127, v48, v57
	v_add_f32_e32 v41, 0, v41
	v_lshlrev_b32_e32 v43, 16, v81
	v_add_f32_e32 v43, 0, v43
	v_lshlrev_b32_e32 v50, 16, v82
	v_mul_f32_e32 v102, v48, v40
	v_lshlrev_b32_e32 v40, 16, v80
	v_add_f32_e32 v50, 0, v50
	v_and_b32_e32 v51, 0xffff0000, v82
	v_add_f32_e32 v40, 0, v40
	v_add_f32_e32 v51, 0, v51
	v_fmac_f32_e32 v42, v109, v109
	v_fmac_f32_e32 v42, v110, v110
	v_mul_f32_e32 v125, v48, v56
	v_and_b32_e32 v56, 0xffff0000, v81
	v_fmac_f32_e32 v42, v111, v111
	v_mul_f32_e32 v97, v48, v97
	v_add_f32_e32 v56, 0, v56
	v_fmac_f32_e32 v42, v97, v97
	v_fmac_f32_e32 v42, v112, v112
	v_fmac_f32_e32 v42, v102, v102
	v_fmac_f32_e32 v42, v103, v103
	s_waitcnt vmcnt(3)
	v_lshlrev_b32_e32 v57, 16, v52
	v_and_b32_e32 v52, 0xffff0000, v52
	v_add_f32_e32 v41, v41, v52
	v_lshlrev_b32_e32 v52, 16, v53
	v_add_f32_e32 v43, v43, v52
	v_and_b32_e32 v52, 0xffff0000, v53
	v_lshlrev_b32_e32 v53, 16, v54
	v_add_f32_e32 v50, v50, v53
	v_and_b32_e32 v53, 0xffff0000, v54
	v_add_f32_e32 v40, v40, v57
	v_add_f32_e32 v51, v51, v53
	s_waitcnt vmcnt(2)
	v_lshlrev_b32_e32 v53, 16, v84
	v_add_f32_e32 v40, v40, v53
	v_and_b32_e32 v53, 0xffff0000, v84
	v_add_f32_e32 v41, v41, v53
	v_lshlrev_b32_e32 v53, 16, v85
	v_add_f32_e32 v52, v56, v52
	v_add_f32_e32 v43, v43, v53
	v_and_b32_e32 v53, 0xffff0000, v85
	v_add_f32_e32 v52, v52, v53
	v_lshlrev_b32_e32 v53, 16, v86
	v_add_f32_e32 v50, v50, v53
	v_and_b32_e32 v53, 0xffff0000, v86
	v_add_f32_e32 v51, v51, v53
	s_waitcnt vmcnt(1)
	v_lshlrev_b32_e32 v53, 16, v88
	v_fmac_f32_e32 v42, v104, v104
	v_add_f32_e32 v40, v40, v53
	v_and_b32_e32 v53, 0xffff0000, v88
	v_fmac_f32_e32 v42, v105, v105
	v_add_f32_e32 v41, v41, v53
	v_lshlrev_b32_e32 v53, 16, v89
	v_fmac_f32_e32 v42, v123, v123
	v_add_f32_e32 v43, v43, v53
	v_and_b32_e32 v53, 0xffff0000, v89
	v_fmac_f32_e32 v42, v125, v125
	v_add_f32_e32 v52, v52, v53
	v_lshlrev_b32_e32 v53, 16, v90
	v_fmac_f32_e32 v42, v127, v127
	v_add_f32_e32 v50, v50, v53
	v_and_b32_e32 v53, 0xffff0000, v90
	v_fmac_f32_e32 v42, v129, v129
	v_add_f32_e32 v51, v51, v53
	v_mul_f32_e32 v131, v48, v40
	v_mul_f32_e32 v133, v48, v41
	v_and_b32_e32 v40, 0xffff0000, v83
	v_lshlrev_b32_e32 v41, 16, v83
	v_fmac_f32_e32 v42, v131, v131
	v_mul_f32_e32 v139, v48, v50
	v_mul_f32_e32 v141, v48, v51
	v_pk_add_f32 v[40:41], v[40:41], 0 op_sel_hi:[1,0]
	v_and_b32_e32 v50, 0xffff0000, v55
	v_lshlrev_b32_e32 v51, 16, v55
	v_fmac_f32_e32 v42, v133, v133
	v_mul_f32_e32 v135, v48, v43
	v_pk_add_f32 v[40:41], v[40:41], v[50:51]
	v_and_b32_e32 v50, 0xffff0000, v87
	v_lshlrev_b32_e32 v51, 16, v87
	v_fmac_f32_e32 v42, v135, v135
	v_mul_f32_e32 v137, v48, v52
	v_pk_add_f32 v[40:41], v[40:41], v[50:51]
	v_and_b32_e32 v50, 0xffff0000, v91
	v_lshlrev_b32_e32 v51, 16, v91
	v_fmac_f32_e32 v42, v137, v137
	v_pk_add_f32 v[40:41], v[40:41], v[50:51]
	v_fmac_f32_e32 v42, v139, v139
	v_pk_mul_f32 v[40:41], v[48:49], v[40:41] op_sel_hi:[0,1]
	v_fmac_f32_e32 v42, v141, v141
	v_pk_mul_f32 v[50:51], v[40:41], v[40:41]
	v_lshlrev_b32_e32 v43, 16, v28
	v_add_f32_e32 v42, v51, v42
	v_add_f32_e32 v82, v50, v42
	global_load_dwordx4 v[50:53], v[120:121], off offset:16
	global_load_dwordx4 v[54:57], v[120:121], off
	global_load_dwordx4 v[214:217], v[120:121], off offset:64
	global_load_dwordx4 v[218:221], v[120:121], off offset:80
	global_load_dwordx4 v[222:225], v[120:121], off offset:128
	global_load_dwordx4 v[226:229], v[120:121], off offset:144
	global_load_dwordx4 v[230:233], v[120:121], off offset:192
	global_load_dwordx4 v[234:237], v[120:121], off offset:208
	global_load_dwordx4 v[238:241], v[120:121], off offset:256
	global_load_dwordx4 v[242:245], v[120:121], off offset:272
	global_load_dwordx4 v[246:249], v[120:121], off offset:320
	v_and_b32_e32 v42, 0xffff0000, v28
	v_pk_add_f32 v[42:43], v[42:43], 0 op_sel_hi:[1,0]
	v_and_b32_e32 v80, 0xffff0000, v32
	v_lshlrev_b32_e32 v81, 16, v32
	v_pk_add_f32 v[42:43], v[42:43], v[80:81]
	v_and_b32_e32 v80, 0xffff0000, v36
	v_lshlrev_b32_e32 v81, 16, v36
	v_pk_add_f32 v[42:43], v[42:43], v[80:81]
	s_waitcnt vmcnt(11)
	v_and_b32_e32 v80, 0xffff0000, v98
	v_lshlrev_b32_e32 v81, 16, v98
	v_pk_add_f32 v[42:43], v[42:43], v[80:81]
	v_and_b32_e32 v32, 0xffff0000, v33
	v_pk_mul_f32 v[42:43], v[48:49], v[42:43] op_sel_hi:[0,1]
	v_pk_mul_f32 v[80:81], v[42:43], v[42:43]
	v_lshlrev_b32_e32 v33, 16, v33
	v_add_f32_e32 v28, v81, v82
	v_add_f32_e32 v36, v80, v28
	v_and_b32_e32 v28, 0xffff0000, v29
	v_lshlrev_b32_e32 v29, 16, v29
	v_pk_add_f32 v[28:29], v[28:29], 0 op_sel_hi:[1,0]
	ds_write_b128 v173, v[0:3]
	ds_write_b128 v174, v[4:7]
	ds_write_b128 v175, v[8:11]
	ds_write_b128 v176, v[16:19]
	v_pk_add_f32 v[28:29], v[28:29], v[32:33]
	v_and_b32_e32 v32, 0xffff0000, v37
	v_lshlrev_b32_e32 v33, 16, v37
	v_pk_add_f32 v[28:29], v[28:29], v[32:33]
	v_and_b32_e32 v32, 0xffff0000, v99
	v_lshlrev_b32_e32 v33, 16, v99
	v_pk_add_f32 v[28:29], v[28:29], v[32:33]
	v_lshlrev_b32_e32 v37, 16, v34
	v_pk_mul_f32 v[28:29], v[48:49], v[28:29] op_sel_hi:[0,1]
	v_pk_mul_f32 v[32:33], v[28:29], v[28:29]
	ds_write_b128 v177, v[12:15]
	ds_write_b128 v178, v[20:23]
	ds_write_b128 v179, v[24:27]
	v_add_f32_e32 v33, v33, v36
	v_add_f32_e32 v80, v32, v33
	v_and_b32_e32 v32, 0xffff0000, v30
	v_lshlrev_b32_e32 v33, 16, v30
	v_pk_add_f32 v[32:33], v[32:33], 0 op_sel_hi:[1,0]
	v_and_b32_e32 v36, 0xffff0000, v34
	v_pk_add_f32 v[32:33], v[32:33], v[36:37]
	v_and_b32_e32 v36, 0xffff0000, v38
	v_lshlrev_b32_e32 v37, 16, v38
	v_pk_add_f32 v[32:33], v[32:33], v[36:37]
	v_and_b32_e32 v36, 0xffff0000, v100
	v_lshlrev_b32_e32 v37, 16, v100
	v_pk_add_f32 v[32:33], v[32:33], v[36:37]
	v_and_b32_e32 v34, 0xffff0000, v35
	v_pk_mul_f32 v[32:33], v[48:49], v[32:33] op_sel_hi:[0,1]
	v_pk_mul_f32 v[36:37], v[32:33], v[32:33]
	v_lshlrev_b32_e32 v35, 16, v35
	v_add_f32_e32 v30, v37, v80
	v_add_f32_e32 v36, v36, v30
	v_and_b32_e32 v30, 0xffff0000, v31
	v_lshlrev_b32_e32 v31, 16, v31
	v_pk_add_f32 v[30:31], v[30:31], 0 op_sel_hi:[1,0]
	v_mov_b32_e32 v10, v113
	v_pk_add_f32 v[30:31], v[30:31], v[34:35]
	v_and_b32_e32 v34, 0xffff0000, v39
	v_lshlrev_b32_e32 v35, 16, v39
	v_pk_add_f32 v[30:31], v[30:31], v[34:35]
	v_and_b32_e32 v34, 0xffff0000, v101
	v_lshlrev_b32_e32 v35, 16, v101
	v_pk_add_f32 v[30:31], v[30:31], v[34:35]
	v_mov_b32_e32 v11, v113
	v_pk_mul_f32 v[30:31], v[48:49], v[30:31] op_sel_hi:[0,1]
	v_pk_mul_f32 v[34:35], v[30:31], v[30:31]
	v_mov_b32_e32 v12, v113
	v_add_f32_e32 v35, v35, v36
	v_add_f32_e32 v34, v34, v35
	ds_bpermute_b32 v35, v161, v34
	v_mov_b32_e32 v13, v113
	v_mov_b32_e32 v14, v113
	v_mov_b32_e32 v15, v113
	v_mov_b32_e32 v16, 0
	s_waitcnt lgkmcnt(0)
	v_add_f32_e32 v0, v34, v35
	v_fmamk_f32 v0, v0, 0x3c000000, v180
	v_mul_f32_e32 v1, 0x4b800000, v0
	v_cmp_gt_f32_e32 vcc, s6, v0
	v_mov_b32_e32 v17, v113
	v_mov_b32_e32 v18, v113
	v_cndmask_b32_e32 v0, v0, v1, vcc
	v_rsq_f32_e32 v0, v0
	v_mov_b32_e32 v19, v113
	v_mov_b32_e32 v20, v113
	v_mov_b32_e32 v21, v113
	v_mul_f32_e32 v1, 0x45800000, v0
	v_cndmask_b32_e32 v0, v0, v1, vcc
	v_mul_f32_e32 v8, 0x3db504f3, v0
	v_mul_f32_e32 v0, v58, v8
	v_mul_f32_e32 v1, v49, v8
	v_mul_f32_e32 v2, v59, v8
	v_mul_f32_e32 v3, v60, v8
	v_mul_f32_e32 v4, v61, v8
	v_mul_f32_e32 v5, v62, v8
	v_mul_f32_e32 v6, v63, v8
	v_mul_f32_e32 v7, v64, v8
	s_waitcnt vmcnt(9)
	v_mul_f32_e32 v0, v54, v0
	v_mul_f32_e32 v1, v55, v1
	v_mul_f32_e32 v2, v56, v2
	v_mul_f32_e32 v3, v57, v3
	v_mul_f32_e32 v4, v50, v4
	v_mul_f32_e32 v5, v51, v5
	v_mul_f32_e32 v6, v52, v6
	v_mul_f32_e32 v7, v53, v7
	v_cvt_pk_bf16_f32 v80, v0, v1
	v_cvt_pk_bf16_f32 v81, v2, v3
	v_cvt_pk_bf16_f32 v82, v4, v5
	v_cvt_pk_bf16_f32 v83, v6, v7
	v_mul_f32_e32 v9, v44, v8
	v_mov_b32_e32 v22, v113
	v_mov_b32_e32 v23, v113
	v_mov_b32_e32 v24, v113
	v_mov_b32_e32 v25, v113
	v_mov_b32_e32 v26, v113
	v_mov_b32_e32 v27, v113
	v_mov_b32_e32 v34, v113
	v_mov_b32_e32 v35, v113
	v_mov_b32_e32 v36, v113
	v_mov_b32_e32 v37, v113
	v_mov_b32_e32 v38, v113
	v_mov_b32_e32 v39, v113
	v_mov_b32_e32 v44, v113
	v_mov_b32_e32 v48, 0
	v_mov_b32_e32 v49, v113
	v_mov_b32_e32 v50, v113
	v_mov_b32_e32 v51, v113
	v_mov_b32_e32 v52, v113
	v_mov_b32_e32 v53, v113
	v_mov_b32_e32 v54, v113
	v_mov_b32_e32 v55, v113
	v_mov_b32_e32 v56, v113
	v_mov_b32_e32 v57, v113
	v_mov_b32_e32 v58, v113
	v_mov_b32_e32 v59, v113
	v_mov_b32_e32 v60, v113
	v_mov_b32_e32 v61, v113
	v_mov_b32_e32 v62, v113
	v_mov_b32_e32 v63, v113
	s_waitcnt vmcnt(8)
	v_mov_b32_e32 v0, v214
	v_mov_b32_e32 v1, v215
	v_mov_b32_e32 v2, v216
	v_mov_b32_e32 v3, v217
	v_mul_f32_e32 v0, v0, v9
	v_mul_f32_e32 v9, v45, v8
	v_mul_f32_e32 v1, v1, v9
	v_mul_f32_e32 v9, v46, v8
	v_mul_f32_e32 v2, v2, v9
	v_mul_f32_e32 v9, v47, v8
	v_mul_f32_e32 v3, v3, v9
	v_mul_f32_e32 v9, v65, v8
	s_waitcnt vmcnt(7)
	v_mov_b32_e32 v4, v218
	v_mov_b32_e32 v5, v219
	v_mov_b32_e32 v6, v220
	v_mov_b32_e32 v7, v221
	global_load_dwordx4 v[214:217], v[120:121], off offset:336
	global_load_dwordx4 v[218:221], v[120:121], off offset:384
	v_mul_f32_e32 v4, v4, v9
	v_mul_f32_e32 v9, v66, v8
	v_mul_f32_e32 v5, v5, v9
	v_mul_f32_e32 v9, v67, v8
	v_mul_f32_e32 v6, v6, v9
	v_mul_f32_e32 v9, v68, v8
	v_mul_f32_e32 v7, v7, v9
	v_cvt_pk_bf16_f32 v84, v0, v1
	v_cvt_pk_bf16_f32 v85, v2, v3
	v_cvt_pk_bf16_f32 v86, v4, v5
	v_cvt_pk_bf16_f32 v87, v6, v7
	v_mul_f32_e32 v9, v69, v8
	v_mov_b32_e32 v45, v113
	v_mov_b32_e32 v46, v113
	v_mov_b32_e32 v47, v113
	s_waitcnt vmcnt(8)
	v_mov_b32_e32 v0, v222
	v_mov_b32_e32 v1, v223
	v_mov_b32_e32 v2, v224
	v_mov_b32_e32 v3, v225
	v_mul_f32_e32 v0, v0, v9
	v_mul_f32_e32 v9, v70, v8
	v_mul_f32_e32 v1, v1, v9
	v_mul_f32_e32 v9, v71, v8
	v_mul_f32_e32 v2, v2, v9
	v_mul_f32_e32 v9, v72, v8
	v_mul_f32_e32 v3, v3, v9
	v_mul_f32_e32 v9, v73, v8
	s_waitcnt vmcnt(7)
	v_mov_b32_e32 v4, v226
	v_mov_b32_e32 v5, v227
	v_mov_b32_e32 v6, v228
	v_mov_b32_e32 v7, v229
	global_load_dwordx4 v[222:225], v[120:121], off offset:400
	global_load_dwordx4 v[226:229], v[120:121], off offset:448
	v_mul_f32_e32 v4, v4, v9
	v_mul_f32_e32 v9, v74, v8
	v_mul_f32_e32 v5, v5, v9
	v_mul_f32_e32 v9, v75, v8
	v_mul_f32_e32 v6, v6, v9
	v_mul_f32_e32 v9, v76, v8
	v_mul_f32_e32 v7, v7, v9
	v_cvt_pk_bf16_f32 v88, v0, v1
	v_cvt_pk_bf16_f32 v89, v2, v3
	v_cvt_pk_bf16_f32 v90, v4, v5
	v_cvt_pk_bf16_f32 v91, v6, v7
	v_mul_f32_e32 v9, v77, v8
	s_waitcnt vmcnt(8)
	v_mov_b32_e32 v0, v230
	v_mov_b32_e32 v1, v231
	v_mov_b32_e32 v2, v232
	v_mov_b32_e32 v3, v233
	v_mul_f32_e32 v0, v0, v9
	v_mul_f32_e32 v9, v78, v8
	v_mul_f32_e32 v1, v1, v9
	v_mul_f32_e32 v9, v79, v8
	v_mul_f32_e32 v2, v2, v9
	v_mul_f32_e32 v9, v92, v8
	v_mul_f32_e32 v3, v3, v9
	v_mul_f32_e32 v9, v93, v8
	s_waitcnt vmcnt(7)
	v_mov_b32_e32 v4, v234
	v_mov_b32_e32 v5, v235
	v_mov_b32_e32 v6, v236
	v_mov_b32_e32 v7, v237
	global_load_dwordx4 v[230:233], v[120:121], off offset:464
	v_mul_f32_e32 v4, v4, v9
	v_mul_f32_e32 v9, v94, v8
	v_mul_f32_e32 v5, v5, v9
	v_mul_f32_e32 v9, v95, v8
	v_mul_f32_e32 v6, v6, v9
	v_mul_f32_e32 v9, v96, v8
	v_mul_f32_e32 v7, v7, v9
	v_cvt_pk_bf16_f32 v92, v0, v1
	v_cvt_pk_bf16_f32 v93, v2, v3
	v_cvt_pk_bf16_f32 v94, v4, v5
	v_cvt_pk_bf16_f32 v95, v6, v7
	v_mul_f32_e32 v9, v106, v8
	s_waitcnt vmcnt(7)
	v_mov_b32_e32 v0, v238
	v_mov_b32_e32 v1, v239
	v_mov_b32_e32 v2, v240
	v_mov_b32_e32 v3, v241
	v_mul_f32_e32 v0, v0, v9
	v_mul_f32_e32 v9, v107, v8
	v_mul_f32_e32 v1, v1, v9
	v_mul_f32_e32 v9, v108, v8
	v_mul_f32_e32 v2, v2, v9
	v_mul_f32_e32 v9, v109, v8
	v_mul_f32_e32 v3, v3, v9
	v_mul_f32_e32 v9, v110, v8
	s_waitcnt vmcnt(6)
	v_mov_b32_e32 v4, v242
	v_mov_b32_e32 v5, v243
	v_mov_b32_e32 v6, v244
	v_mov_b32_e32 v7, v245
	v_mul_f32_e32 v4, v4, v9
	v_mul_f32_e32 v9, v111, v8
	v_mul_f32_e32 v5, v5, v9
	v_mul_f32_e32 v9, v97, v8
	v_mul_f32_e32 v6, v6, v9
	v_mul_f32_e32 v9, v112, v8
	v_mul_f32_e32 v7, v7, v9
	v_cvt_pk_bf16_f32 v96, v0, v1
	v_cvt_pk_bf16_f32 v97, v2, v3
	v_cvt_pk_bf16_f32 v98, v4, v5
	v_cvt_pk_bf16_f32 v99, v6, v7
	v_mul_f32_e32 v9, v102, v8
	v_mov_b32_e32 v112, v163
	s_waitcnt vmcnt(5)
	v_mov_b32_e32 v0, v246
	v_mov_b32_e32 v1, v247
	v_mov_b32_e32 v2, v248
	v_mov_b32_e32 v3, v249
	v_mul_f32_e32 v0, v0, v9
	v_mul_f32_e32 v9, v103, v8
	v_mul_f32_e32 v1, v1, v9
	v_mul_f32_e32 v9, v104, v8
	v_mul_f32_e32 v2, v2, v9
	v_mul_f32_e32 v9, v105, v8
	v_mul_f32_e32 v3, v3, v9
	v_mul_f32_e32 v9, v123, v8
	s_waitcnt vmcnt(4)
	v_mov_b32_e32 v4, v214
	v_mov_b32_e32 v5, v215
	v_mov_b32_e32 v6, v216
	v_mov_b32_e32 v7, v217
	v_mul_f32_e32 v4, v4, v9
	v_mul_f32_e32 v9, v125, v8
	v_mul_f32_e32 v5, v5, v9
	v_mul_f32_e32 v9, v127, v8
	v_mul_f32_e32 v6, v6, v9
	v_mul_f32_e32 v9, v129, v8
	v_mul_f32_e32 v7, v7, v9
	v_cvt_pk_bf16_f32 v100, v0, v1
	v_cvt_pk_bf16_f32 v101, v2, v3
	v_cvt_pk_bf16_f32 v102, v4, v5
	v_cvt_pk_bf16_f32 v103, v6, v7
	v_mul_f32_e32 v9, v131, v8
	v_mov_b32_e32 v127, 0xff800000
	v_mov_b32_e32 v123, v162
	v_mov_b32_e32 v125, 0
	s_waitcnt vmcnt(3)
	v_mov_b32_e32 v0, v218
	v_mov_b32_e32 v1, v219
	v_mov_b32_e32 v2, v220
	v_mov_b32_e32 v3, v221
	v_mul_f32_e32 v0, v0, v9
	v_mul_f32_e32 v9, v133, v8
	v_mul_f32_e32 v1, v1, v9
	v_mul_f32_e32 v9, v135, v8
	v_mul_f32_e32 v2, v2, v9
	v_mul_f32_e32 v9, v137, v8
	v_mul_f32_e32 v3, v3, v9
	v_mul_f32_e32 v9, v139, v8
	s_waitcnt vmcnt(2)
	v_mov_b32_e32 v4, v222
	v_mov_b32_e32 v5, v223
	v_mov_b32_e32 v6, v224
	v_mov_b32_e32 v7, v225
	v_mul_f32_e32 v4, v4, v9
	v_mul_f32_e32 v9, v141, v8
	v_mul_f32_e32 v5, v5, v9
	v_mul_f32_e32 v9, v41, v8
	v_mul_f32_e32 v6, v6, v9
	v_mul_f32_e32 v9, v40, v8
	v_mul_f32_e32 v7, v7, v9
	v_cvt_pk_bf16_f32 v104, v0, v1
	v_cvt_pk_bf16_f32 v105, v2, v3
	v_cvt_pk_bf16_f32 v106, v4, v5
	v_cvt_pk_bf16_f32 v107, v6, v7
	v_mul_f32_e32 v9, v43, v8
	v_mov_b32_e32 v40, v113
	v_mov_b32_e32 v41, v113
	v_mov_b32_e32 v43, v113
	s_waitcnt vmcnt(1)
	v_mov_b32_e32 v0, v226
	v_mov_b32_e32 v1, v227
	v_mov_b32_e32 v2, v228
	v_mov_b32_e32 v3, v229
	v_mul_f32_e32 v0, v0, v9
	v_mul_f32_e32 v9, v42, v8
	v_mul_f32_e32 v1, v1, v9
	v_mul_f32_e32 v9, v29, v8
	v_mul_f32_e32 v2, v2, v9
	v_mul_f32_e32 v9, v28, v8
	v_mul_f32_e32 v3, v3, v9
	v_mul_f32_e32 v9, v33, v8
	s_waitcnt vmcnt(0)
	v_mov_b32_e32 v4, v230
	v_mov_b32_e32 v5, v231
	v_mov_b32_e32 v6, v232
	v_mov_b32_e32 v7, v233
	v_mul_f32_e32 v4, v4, v9
	v_mul_f32_e32 v9, v32, v8
	v_mul_f32_e32 v5, v5, v9
	v_mul_f32_e32 v9, v31, v8
	v_mul_f32_e32 v8, v30, v8
	v_mul_f32_e32 v6, v6, v9
	v_mul_f32_e32 v7, v7, v8
	v_cvt_pk_bf16_f32 v108, v0, v1
	v_cvt_pk_bf16_f32 v109, v2, v3
	v_cvt_pk_bf16_f32 v110, v4, v5
	v_cvt_pk_bf16_f32 v111, v6, v7
	v_mov_b32_e32 v0, 0
	v_mov_b32_e32 v1, v113
	v_mov_b32_e32 v2, v113
	v_mov_b32_e32 v3, v113
	v_mov_b32_e32 v4, v113
	v_mov_b32_e32 v5, v113
	v_mov_b32_e32 v6, v113
	v_mov_b32_e32 v7, v113
	v_mov_b32_e32 v8, v113
	v_mov_b32_e32 v9, v113
	v_mov_b32_e32 v28, v113
	v_mov_b32_e32 v29, v113
	v_mov_b32_e32 v30, v113
	v_mov_b32_e32 v31, v113
	v_mov_b32_e32 v32, 0
	v_mov_b32_e32 v33, v113
	v_mov_b32_e32 v42, v113
	s_barrier
